# bundle: swiglu epilogue write-back stores (L2 writeback kept after swiglu phases), K-loop s_setprio toggles removed, attention sink/V loads overlapped with first round trip
# speedup vs baseline: 1.0061x; 1.0061x over previous
.LBB0_605:
	s_waitcnt vmcnt(0)
	s_waitcnt vmcnt(0) lgkmcnt(0)
	s_barrier
	s_and_saveexec_b64 s[4:5], s[88:89]
	v_readlane_b32 s22, v249, 57
	v_readlane_b32 s24, v249, 59
	v_readlane_b32 s26, v249, 61
	v_readlane_b32 s28, v249, 63
	v_readlane_b32 s30, v248, 1
	v_readlane_b32 s34, v248, 3
	v_readlane_b32 s36, v248, 5
	v_readlane_b32 s23, v249, 58
	v_readlane_b32 s25, v249, 60
	v_readlane_b32 s27, v249, 62
	v_readlane_b32 s29, v248, 0
	v_readlane_b32 s31, v248, 2
	v_readlane_b32 s35, v248, 4
	v_readlane_b32 s37, v248, 6
	v_readlane_b32 s21, v248, 7
	s_cbranch_execz .LBB0_133
	buffer_inv sc1
	v_readlane_b32 s6, v249, 50
	v_readlane_b32 s7, v249, 51
	v_readlane_b32 s8, v249, 35
	v_readlane_b32 s9, v249, 36
	v_readlane_b32 s10, v249, 37
	v_readlane_b32 s11, v249, 38
	v_mov_b32_e32 v0, s6
	v_mov_b32_e32 v2, s7
	ds_read_b32 v3, v0
	ds_read_b32 v2, v2
	v_mov_b32_e32 v4, 1
	s_add_i32 s15, s3, 2
	s_nop 2
	global_atomic_add v4, v1, v4, s[8:9] sc0
	s_waitcnt vmcnt(0) lgkmcnt(0)
	v_max_u32_e32 v3, 1, v3
	v_max_u32_e32 v2, 1, v2
	v_readfirstlane_b32 s12, v4
	v_readfirstlane_b32 s13, v3
	v_readfirstlane_b32 s14, v2
	s_mul_i32 s16, s15, s13
	s_add_i32 s12, s12, 1
	s_cmp_lg_u32 s12, s16
	s_cbranch_scc1 .Lb_wait
	s_bitcmp1_b32 0x95254, s3
	s_cbranch_scc1 .Lb_nowb
	buffer_wbl2 sc1
